# v23 plus phase-3 gMLP norm tables in LDS and pooling-first item order on alternate CUs
# speedup vs baseline: 1.0067x; 1.0026x over previous
.LBB0_330:
	s_or_b64 exec, exec, s[0:1]
	s_waitcnt lgkmcnt(0)
	v_mov_b32_e32 v0, v254
	s_cmpk_gt_i32 s2, 0x7ff
	s_barrier
	s_cbranch_scc1 .LBB0_409
	v_bfe_u32 v6, v0, 5, 1
	v_ashrrev_i32_e32 v187, 5, v0
	v_lshlrev_b32_e32 v9, 9, v0
	v_lshlrev_b32_e32 v18, 3, v6
	s_movk_i32 s6, 0xff00
	v_lshlrev_b32_e32 v23, 2, v187
	v_bfe_u32 v1, v0, 2, 2
	v_lshrrev_b32_e32 v2, 3, v0
	v_bfe_u32 v4, v0, 1, 1
	v_and_b32_e32 v7, 31, v0
	v_bfe_u32 v149, v0, 6, 2
	v_ashrrev_i32_e32 v8, 8, v0
	v_and_b32_e32 v9, 0x2000, v9
	v_and_b32_e32 v10, 15, v0
	v_bfe_u32 v11, v187, 2, 2
	v_ashrrev_i32_e32 v12, 2, v0
	v_lshlrev_b32_e32 v13, 7, v0
	v_lshlrev_b32_e32 v14, 12, v0
	v_lshlrev_b32_e32 v15, 3, v0
	v_and_b32_e32 v17, 12, v0
	v_and_or_b32 v19, v0, s6, v18
	v_lshlrev_b32_e32 v0, 9, v187
	v_and_b32_e32 v23, 12, v23
	v_add_u32_e32 v9, 0, v9
	v_and_b32_e32 v21, 0xffffc000, v0
	v_lshlrev_b32_e32 v22, 8, v187
	v_bitop3_b32 v23, v23, v10, v11 bitop3:0x36
	v_add_u32_e32 v21, v9, v21
	v_and_b32_e32 v22, 0x1f00, v22
	v_lshlrev_b32_e32 v23, 4, v23
	v_add3_u32 v189, v21, v23, v22
	v_add_u32_e32 v21, 16, v187
	v_lshlrev_b32_e32 v24, 9, v21
	v_and_b32_e32 v25, 31, v21
	v_lshlrev_b32_e32 v21, 2, v21
	v_and_b32_e32 v21, 12, v21
	v_and_b32_e32 v24, 0xffffc000, v24
	v_bitop3_b32 v21, v21, v10, v11 bitop3:0x36
	v_add_u32_e32 v24, v9, v24
	v_lshlrev_b32_e32 v25, 8, v25
	v_lshlrev_b32_e32 v21, 4, v21
	v_add3_u32 v191, v24, v21, v25
	v_add_u32_e32 v21, 0x4000, v0
	v_and_b32_e32 v21, 0xffffc000, v21
	v_add_u32_e32 v21, v9, v21
	v_add3_u32 v192, v21, v23, v22
	v_add_u32_e32 v21, 48, v187
	v_lshlrev_b32_e32 v24, 9, v21
	v_and_b32_e32 v25, 31, v21
	v_lshlrev_b32_e32 v21, 2, v21
	v_and_b32_e32 v21, 12, v21
	v_and_b32_e32 v24, 0xffffc000, v24
	v_bitop3_b32 v21, v21, v10, v11 bitop3:0x36
	v_add_u32_e32 v24, v9, v24
	v_lshlrev_b32_e32 v25, 8, v25
	v_lshlrev_b32_e32 v21, 4, v21
	v_add3_u32 v193, v24, v21, v25
	v_add_u32_e32 v21, 0x8000, v0
	v_and_b32_e32 v21, 0xffffc000, v21
	v_add_u32_e32 v21, v9, v21
	v_add3_u32 v194, v21, v23, v22
	v_add_u32_e32 v21, 0x50, v187
	v_lshlrev_b32_e32 v24, 9, v21
	v_and_b32_e32 v25, 31, v21
	v_lshlrev_b32_e32 v21, 2, v21
	v_add_u32_e32 v0, 0xc000, v0
	v_and_b32_e32 v21, 12, v21
	v_and_b32_e32 v0, 0xffffc000, v0
	v_and_b32_e32 v24, 0xffffc000, v24
	v_bitop3_b32 v21, v21, v10, v11 bitop3:0x36
	v_add_u32_e32 v0, v9, v0
	v_add_u32_e32 v24, v9, v24
	v_lshlrev_b32_e32 v25, 8, v25
	v_lshlrev_b32_e32 v21, 4, v21
	v_add3_u32 v196, v0, v23, v22
	v_add_u32_e32 v0, 0x70, v187
	v_add3_u32 v195, v24, v21, v25
	v_lshlrev_b32_e32 v21, 9, v0
	v_and_b32_e32 v21, 0xffffc000, v21
	v_add_u32_e32 v9, v9, v21
	v_and_b32_e32 v21, 31, v0
	v_lshlrev_b32_e32 v0, 2, v0
	v_and_b32_e32 v0, 12, v0
	v_bitop3_b32 v0, v0, v10, v11 bitop3:0x36
	v_and_b32_e32 v15, 8, v15
	v_lshlrev_b32_e32 v16, 8, v12
	v_bfe_u32 v12, v12, 2, 2
	v_lshlrev_b32_e32 v21, 8, v21
	v_lshlrev_b32_e32 v0, 4, v0
	v_add3_u32 v197, v9, v0, v21
	v_bitop3_b32 v0, v17, v15, v12 bitop3:0x36
	v_lshlrev_b32_e32 v9, 4, v0
	v_or_b32_e32 v0, 1, v15
	v_bitop3_b32 v0, v17, v0, v12 bitop3:0x36
	v_lshlrev_b32_e32 v10, 4, v0
	v_or_b32_e32 v0, 2, v15
	v_bitop3_b32 v0, v17, v0, v12 bitop3:0x36
	v_lshlrev_b32_e32 v11, 4, v0
	v_or_b32_e32 v0, 3, v15
	v_bitop3_b32 v0, v17, v0, v12 bitop3:0x36
	v_lshlrev_b32_e32 v21, 4, v0
	v_or_b32_e32 v0, 4, v15
	v_and_b32_e32 v13, 0xffffc000, v13
	v_bitop3_b32 v0, v17, v0, v12 bitop3:0x36
	v_add_u32_e32 v13, 0, v13
	v_and_b32_e32 v14, 0x2000, v14
	v_and_b32_e32 v16, 0x1f00, v16
	v_lshlrev_b32_e32 v22, 4, v0
	v_or_b32_e32 v0, 5, v15
	v_add3_u32 v13, v13, v14, v16
	v_lshlrev_b32_e32 v14, 13, v8
	v_lshlrev_b32_e32 v16, 11, v6
	v_bitop3_b32 v0, v17, v0, v12 bitop3:0x36
	v_add3_u32 v14, 0, v14, v16
	v_lshlrev_b32_e32 v16, 8, v1
	v_lshlrev_b32_e32 v23, 4, v0
	v_or_b32_e32 v0, 6, v15
	v_and_b32_e32 v3, 2, v2
	v_add3_u32 v14, v14, v16, v15
	v_lshlrev_b32_e32 v16, 1, v6
	v_bitop3_b32 v0, v17, v0, v12 bitop3:0x36
	s_add_u32 s8, s28, 0x80000
	v_or_b32_e32 v5, v3, v4
	v_lshlrev_b32_e32 v148, 3, v7
	v_bitop3_b32 v3, v3, v16, v4 bitop3:0x36
	v_lshlrev_b32_e32 v4, 7, v8
	v_lshlrev_b32_e32 v24, 4, v0
	v_or_b32_e32 v0, 7, v15
	s_addc_u32 s9, s29, 0
	v_lshl_or_b32 v2, v149, 8, v148
	v_mov_b32_e32 v151, 0
	v_lshlrev_b32_e32 v150, 4, v7
	v_bitop3_b32 v16, v16, v5, 1 bitop3:0x36
	v_ashrrev_i32_e32 v5, 31, v4
	s_add_i32 s0, 0, 0x10000
	v_bitop3_b32 v0, v17, v0, v12 bitop3:0x36
	v_lshl_add_u64 v[152:153], s[70:71], 0, v[150:151]
	v_add_u32_e32 v20, s0, v150
	v_lshlrev_b32_e32 v12, 4, v0
	v_lshlrev_b32_e32 v200, 6, v1
	v_lshlrev_b32_e32 v150, 2, v2
	v_lshlrev_b64 v[0:1], 2, v[4:5]
	v_lshl_or_b32 v188, v149, 5, v7
	s_movk_i32 s1, 0x210
	v_mov_b32_e32 v7, s0
	v_lshl_add_u64 v[154:155], s[62:63], 0, v[150:151]
	v_lshl_add_u64 v[156:157], s[64:65], 0, v[150:151]
	v_lshl_add_u64 v[4:5], s[52:53], 0, v[0:1]
	v_lshlrev_b32_e32 v150, 4, v6
	v_lshl_add_u64 v[0:1], s[54:55], 0, v[0:1]
	v_mad_u32_u24 v7, v188, s1, v7
	v_lshl_add_u32 v198, v3, 4, v14
	v_mul_lo_u32 v3, v187, s1
	v_lshl_add_u64 v[158:159], v[4:5], 0, v[150:151]
	v_lshl_add_u64 v[160:161], v[0:1], 0, v[150:151]
	v_subrev_u32_e32 v246, s52, v158
	v_add_u32_e32 v247, 0x20c00, v246
	v_add_u32_e32 v246, 0x20800, v246
	s_mov_b64 s[98:99], exec
	v_cmp_gt_u32_e32 vcc, 64, v254
	s_and_b64 exec, exec, vcc
	v_lshlrev_b32_e32 v248, 4, v254
	global_load_dwordx4 v[250:253], v248, s[52:53]
	v_add_u32_e32 v249, 0x20800, v248
	s_waitcnt vmcnt(0)
	ds_write_b128 v249, v[250:253]
	global_load_dwordx4 v[250:253], v248, s[54:55]
	v_add_u32_e32 v249, 0x20c00, v248
	s_waitcnt vmcnt(0)
	ds_write_b128 v249, v[250:253]
	s_waitcnt lgkmcnt(0)
	s_mov_b64 exec, s[98:99]
	v_lshl_or_b32 v0, v149, 4, v6
	v_lshlrev_b32_e32 v150, 1, v2
	s_mov_b32 s13, 0
	v_cmp_lt_u32_e64 s[4:5], 1, v149
	s_mov_b32 s3, 0x10000
	s_mov_b32 s51, 0x8000
	s_mov_b32 s66, 0xc000
	v_lshl_add_u32 v199, v16, 4, v14
	v_xor_b32_e32 v201, 64, v200
	v_xor_b32_e32 v202, 0x80, v200
	v_xor_b32_e32 v203, 0xc0, v200
	v_lshl_add_u64 v[162:163], s[18:19], 0, v[150:151]
	v_lshl_or_b32 v204, v8, 4, v18
	s_lshl_b32 s53, s2, 5
	s_lshl_b32 s55, s30, 5
	s_movk_i32 s62, 0x2800
	v_lshlrev_b32_e32 v164, 1, v2
	s_mov_b64 s[24:25], 0x1800
	s_mov_b32 s63, 0xf000
	s_mov_b32 s64, 0x11000
	s_movk_i32 s65, 0x3000
	s_mov_b32 s67, 0xd000
	s_mov_b32 s70, 0x12000
	s_mov_b32 s50, 0x3e000000
	s_mov_b32 s52, 0x3e800000
	v_lshlrev_b32_e32 v205, 9, v0
	s_movk_i32 s71, 0x1000
	s_mov_b32 s72, 0x28000
	s_mov_b32 s73, 0x50000
	s_mov_b32 s74, 0x78000
	s_mov_b32 s75, 0xa0000
	s_mov_b32 s76, 0xc8000
	s_mov_b32 s77, 0xf0000
	s_mov_b32 s78, 0x118000
	v_add_u32_e32 v206, v13, v9
	v_add_u32_e32 v207, v13, v10
	v_add_u32_e32 v208, v13, v11
	v_add_u32_e32 v209, v13, v24
	v_add_u32_e32 v210, v13, v21
	v_add_u32_e32 v211, v13, v22
	v_add_u32_e32 v212, v13, v23
	v_add_u32_e32 v213, v13, v12
	s_mov_b32 s54, 0x3b800000
	s_mov_b32 s79, 0x800000
	s_mov_b32 s80, 0x29000
	s_mov_b32 s81, 0x51000
	s_mov_b32 s82, 0x79000
	s_mov_b32 s83, 0xa1000
	s_mov_b32 s84, 0xc9000
	s_mov_b32 s85, 0xf1000
	s_mov_b32 s86, 0x119000
	v_add_u32_e32 v214, v7, v19
	v_add_u32_e32 v215, v20, v3
	s_mov_b32 s87, 0x20000
	s_mov_b32 s88, 0x30000
	s_mov_b32 s89, 0x40000
	s_mov_b32 s90, 0x60000
	v_mbcnt_hi_u32_b32 v216, -1, v186
	s_mov_b32 s91, s2
	s_mov_b32 s98, 0
	s_mov_b32 s99, 0
	s_cmp_lg_u32 s30, 0x100
	s_cbranch_scc1 .LBB0_334
	s_bitcmp0_b32 s2, 3
	s_cbranch_scc1 .LBB0_334
	s_mov_b32 s98, 1
	s_mov_b32 s99, 1
	s_add_i32 s91, s91, 0x400
	s_add_i32 s53, s53, 0x8000
	s_branch .LBB0_334
